# P9 rounds 0-1 | seam | P9 round 2 on CUs 0-127 beside a 2-wave-per-CU final RMSNorm of finished row tiles on CUs 128-255 | seam | rest of final RMSNorm
# speedup vs baseline: 1.0088x; 1.0010x over previous
_ZN2pb8mega_fwdENS_4ArgsE:
	s_load_dwordx8 s[4:11], s[0:1], 0xc0
	s_load_dwordx4 s[76:79], s[0:1], 0xe0
	s_load_dwordx2 s[82:83], s[0:1], 0xf0
	s_load_dword s33, s[0:1], 0x100
	v_and_b32_e32 v210, 0x3ff, v0
	s_mov_b32 s91, s2
	s_mov_b32 s101, s2
	s_mov_b32 s100, 0
	s_mov_b32 s101, s2
	s_mov_b32 s100, 0
	v_readfirstlane_b32 s3, v210
	s_waitcnt lgkmcnt(0)
	v_writelane_b32 v254, s4, 0
	s_nop 1
	v_writelane_b32 v254, s5, 1
	v_writelane_b32 v254, s6, 2
	v_writelane_b32 v254, s7, 3
	v_writelane_b32 v254, s8, 4
	v_writelane_b32 v254, s9, 5
	v_writelane_b32 v254, s10, 6
	v_writelane_b32 v254, s11, 7
	s_add_u32 s4, s0, 0x100
	s_addc_u32 s5, s1, 0
	v_writelane_b32 v254, s4, 8
	s_nop 1
	v_writelane_b32 v254, s5, 9
	s_and_b32 s4, s33, 7
	s_cmp_lg_u32 s4, 0
	s_cbranch_scc0 .LBB0_98
	v_cmp_gt_u32_e32 vcc, 2, v210
	s_and_saveexec_b64 s[4:5], vcc

.Lp10a:
	v_readlane_b32 s2, v254, 6
	v_readlane_b32 s3, v254, 7
	v_and_b32_e32 v0, 63, v210
	v_readfirstlane_b32 s0, v210
	v_lshlrev_b32_e32 v1, 3, v0
	v_lshlrev_b32_e32 v2, 4, v0
	v_mov_b32_e32 v3, 0x3a800000
	v_mov_b32_e32 v121, 0x358637bd
	s_lshr_b32 s0, s0, 6
	global_load_dwordx4 v[4:7], v2, s[2:3]
	global_load_dwordx4 v[8:11], v2, s[2:3] offset:1024
	global_load_dwordx4 v[12:15], v2, s[2:3] offset:2048
	global_load_dwordx4 v[16:19], v2, s[2:3] offset:3072
	s_sub_i32 s1, s101, 128
	s_lshr_b32 s4, s1, 4
	s_bfe_u32 s5, s1, 0x30001
	s_cmp_lt_u32 s4, 4
	s_cselect_b32 s4, 4, 0xff
	s_cmp_eq_u32 s5, s4
	s_cbranch_scc1 .Lp10a_done
	s_lshr_b32 s4, s1, 4
	s_mul_i32 s4, s4, 20
	s_and_b32 s5, s1, 15
	s_add_i32 s4, s4, s5
	s_lshl_b32 s4, s4, 8
	s_cmp_gt_u32 s0, 1
	s_cbranch_scc1 .Lp10a_done
	s_lshl_b32 s5, s0, 7
	s_add_i32 s4, s4, s5
	s_movk_i32 s10, 32
	s_lshl_b32 s5, s4, 11
	s_add_u32 s12, s78, s5
	s_addc_u32 s13, s79, 0
	s_add_u32 s12, s12, 0x2000000
	s_addc_u32 s13, s13, 0
	s_lshl_b32 s5, s4, 12
	s_add_u32 s14, s76, s5
	s_addc_u32 s15, s77, 0
